# prepD: the 4-load wait/convert ladder in the q/k branch now loads into private temps and is converted after the following 14 loads are in flight (one memory round trip fewer per task round)
# speedup vs baseline: 1.0013x; 1.0013x over previous
; DI float bf2f(bf16_t b) { return __uint_as_float(((unsigned)b) << 16); }
; NI void prepD_row(const P& p, int l, int t0) {
;     ...
;     if (task < 8) {
;       if (isq) {
;         const bf16_t* src = (const bf16_t*)(ws + WS_QDR) + (size_t)t0 * 768 + hd * 192 + ln;
; #pragma unroll
;         for (int rr = 0; rr < RBD; ++rr)
; #pragma unroll
;           for (int j = 0; j < 6; ++j) x[rr][j] = bf2f(src[(size_t)rr * 768 + 32 * j]);
;       } else {
;         const bf16_t* src = (const bf16_t*)(ws + WS_KVDR) + (size_t)t0 * 1024 + hd * 256 + ln;
; #pragma unroll
;         for (int rr = 0; rr < RBD; ++rr) {
; #pragma unroll
;           for (int j = 0; j < 4; ++j) x[rr][j] = bf2f(src[(size_t)rr * 1024 + 32 * j]);
;           x[rr][4] = bf2f(U[(size_t)(t0 + rr) * INP + O_DKR + ln]); x[rr][5] = bf2f(U[(size_t)(t0 + rr) * INP + O_DKR + 32 + ln]);
;         }
;       }
.LBB0_187:
	s_or_b64 exec, exec, s[18:19]
	global_load_ushort v115, v[90:91], off
	global_load_ushort v114, v[92:93], off
	global_load_ushort v113, v[94:95], off
	v_cmp_lt_i32_e64 s[26:27], 7, v106
	v_cmp_gt_i32_e32 vcc, 8, v106
	v_mov_b32_e32 v90, 0
	v_mov_b64_e32 v[104:105], v[30:31]
	v_mov_b64_e32 v[92:93], v[28:29]
	v_mov_b64_e32 v[98:99], v[26:27]
	v_mov_b64_e32 v[100:101], v[24:25]
	v_mov_b64_e32 v[102:103], v[22:23]
	v_mov_b32_e32 v91, 0
	v_mov_b32_e32 v94, 0
	v_mov_b32_e32 v95, 0
	v_mov_b32_e32 v200, 0
	v_mov_b32_e32 v201, 0
	v_mov_b32_e32 v202, 0
	v_mov_b32_e32 v203, 0
	s_and_saveexec_b64 s[18:19], vcc
	s_cbranch_execz .LBB0_193
	s_and_saveexec_b64 s[28:29], s[24:25]
	s_xor_b64 s[28:29], exec, s[28:29]
	s_cbranch_execz .LBB0_190
	global_load_ushort v200, v[36:37], off
	global_load_ushort v201, v[34:35], off
	global_load_ushort v202, v[48:49], off
	global_load_ushort v203, v[46:47], off
.LBB0_190:
	s_or_saveexec_b64 s[28:29], s[28:29]
	v_mov_b64_e32 v[102:103], v[32:33]
	v_mov_b64_e32 v[100:101], v[38:39]
	v_mov_b64_e32 v[98:99], v[40:41]
	v_mov_b64_e32 v[92:93], v[42:43]
	v_mov_b64_e32 v[104:105], v[44:45]
	s_xor_b64 exec, exec, s[28:29]
	s_cbranch_execz .LBB0_192
	global_load_ushort v200, v[50:51], off offset:320
	global_load_ushort v201, v[50:51], off offset:256
	global_load_ushort v202, v[50:51], off offset:1856
	global_load_ushort v203, v[50:51], off offset:1792
	v_mov_b64_e32 v[102:103], v[50:51]
	v_mov_b64_e32 v[100:101], v[52:53]
	v_mov_b64_e32 v[98:99], v[54:55]
	v_mov_b64_e32 v[92:93], v[56:57]
	v_mov_b64_e32 v[104:105], v[58:59]

; DI float bf2f(bf16_t b) { return __uint_as_float(((unsigned)b) << 16); }
; NI void prepD_row(const P& p, int l, int t0) {
;     ...
;           x[rr][4] = bf2f(U[(size_t)(t0 + rr) * INP + O_DKR + ln]); x[rr][5] = bf2f(U[(size_t)(t0 + rr) * INP + O_DKR + 32 + ln]);
;         }
;       }
;     } else {
;       const bf16_t* src = (const bf16_t*)(ws + WS_KVDR) + (size_t)t0 * 1024 + hd * 256 + 128 + ln;
; #pragma unroll
;       for (int rr = 0; rr < RBD; ++rr) {
; #pragma unroll
;         for (int j = 0; j < 4; ++j) x[rr][j] = bf2f(src[(size_t)rr * 1024 + 32 * j]);
;         x[rr][4] = 0.f; x[rr][5] = 0.f;
;       }
;     }
;     float nwv[6];
;     const float* nwp = (isq ? p.in[I_MQQK] : p.in[I_MKQK]) + l * 192 + ln;
; #pragma unroll
;     for (int j = 0; j < 6; ++j) nwv[j] = nwp[32 * j];
;     const float invf = exp2f(-(float)(ln & 15) * (13.287712379549449f / 16.f));
; #pragma unroll
;     for (int rr = 0; rr < RBD; ++rr) {
;       const int t = t0 + rr;
;       const float rstd_in = rsqrtf(hw_sum(ssi[rr]) * (isq ? (1.f / 384.f) : (1.f / 256.f)) + EPS);
.LBB0_193:
	s_or_b64 exec, exec, s[18:19]
	v_readlane_b32 s40, v252, 4
	v_readlane_b32 s45, v252, 9
	v_readlane_b32 s47, v252, 11
	global_load_ushort v89, v[102:103], off
	global_load_ushort v122, v[102:103], off offset:64
	global_load_ushort v123, v[102:103], off offset:128
	s_nop 0
	global_load_ushort v102, v[102:103], off offset:192
	s_nop 0
	global_load_ushort v120, v[100:101], off
	global_load_ushort v117, v[98:99], off
	global_load_ushort v118, v[92:93], off
	global_load_ushort v119, v[104:105], off
	v_readlane_b32 s44, v252, 8
	v_readlane_b32 s46, v252, 10
	v_mov_b32_e32 v92, s47
	v_mov_b32_e32 v93, s45
	v_cndmask_b32_e64 v93, v92, v93, s[22:23]
	v_mov_b32_e32 v92, s46
	v_mov_b32_e32 v98, s44
	v_cndmask_b32_e64 v92, v92, v98, s[22:23]
	v_lshl_add_u64 v[92:93], s[2:3], 2, v[92:93]
	v_lshl_add_u64 v[98:99], v[92:93], 0, v[96:97]
	global_load_dword v103, v[98:99], off
	global_load_dword v104, v[98:99], off offset:128
	global_load_dword v105, v[98:99], off offset:256
	global_load_dword v116, v[98:99], off offset:384
	global_load_dword v93, v[98:99], off offset:512
	global_load_dword v92, v[98:99], off offset:640
	s_waitcnt vmcnt(14)
	v_lshlrev_b32_e32 v94, 16, v200
	v_lshlrev_b32_e32 v95, 16, v201
	v_lshlrev_b32_e32 v90, 16, v202
	v_lshlrev_b32_e32 v91, 16, v203
	ds_bpermute_b32 v98, v107, v88
	v_cndmask_b32_e64 v121, v229, v230, s[22:23]
	v_readlane_b32 s41, v252, 5
	v_readlane_b32 s42, v252, 6
	v_readlane_b32 s43, v252, 7
	s_waitcnt lgkmcnt(0)
	v_add_f32_e32 v88, v88, v98
	s_nop 1
	v_add_f32_dpp v88, v88, v88 row_ror:8 row_mask:0xf bank_mask:0xf
	s_nop 1
	v_add_f32_dpp v88, v88, v88 row_ror:4 row_mask:0xf bank_mask:0xf
	s_nop 1
	v_add_f32_dpp v88, v88, v88 row_ror:2 row_mask:0xf bank_mask:0xf
	s_nop 1
	v_add_f32_dpp v88, v88, v88 row_ror:1 row_mask:0xf bank_mask:0xf
	v_fmaak_f32 v88, v121, v88, 0x358637bd
	v_mul_f32_e32 v98, 0x4b800000, v88
	v_cmp_gt_f32_e32 vcc, s77, v88
	s_waitcnt vmcnt(13)
	v_lshlrev_b32_e32 v89, 16, v89
	v_cndmask_b32_e32 v88, v88, v98, vcc
	v_rsq_f32_e32 v88, v88
	s_waitcnt vmcnt(12)
	v_lshlrev_b32_e32 v99, 16, v122
	s_waitcnt vmcnt(10)
	v_lshlrev_b32_e32 v100, 16, v102
	v_lshlrev_b32_e32 v101, 16, v123
	v_mul_f32_e32 v98, 0x45800000, v88
	v_cndmask_b32_e32 v102, v88, v98, vcc
	v_mul_f32_e32 v98, v102, v89
	v_mul_f32_e32 v99, v102, v99
	s_and_saveexec_b64 s[18:19], s[26:27]
	s_xor_b64 s[18:19], exec, s[18:19]
	s_cbranch_execz .LBB0_195
	v_bfe_u32 v88, v98, 16, 1
	v_add3_u32 v88, v98, v88, s61
	global_store_short_d16_hi v[60:61], v88, off
	v_bfe_u32 v88, v99, 16, 1
	v_add3_u32 v88, v99, v88, s61
	global_store_short_d16_hi v[62:63], v88, off
	v_mul_f32_e32 v88, v102, v101
	v_bfe_u32 v89, v88, 16, 1
	v_add3_u32 v88, v88, v89, s61
	global_store_short_d16_hi v[64:65], v88, off
	v_mul_f32_e32 v88, v102, v100
	v_bfe_u32 v89, v88, 16, 1
	v_add3_u32 v88, v88, v89, s61
	global_store_short_d16_hi v[66:67], v88, off

; DI float bf2f(bf16_t b) { return __uint_as_float(((unsigned)b) << 16); }
; NI void prepD_row(const P& p, int l, int t0) {
;     ...
;           x[rr][4] = bf2f(U[(size_t)(t0 + rr) * INP + O_DKR + ln]); x[rr][5] = bf2f(U[(size_t)(t0 + rr) * INP + O_DKR + 32 + ln]);
;         }
;       }
;     } else {
;       const bf16_t* src = (const bf16_t*)(ws + WS_KVDR) + (size_t)t0 * 1024 + hd * 256 + 128 + ln;
; #pragma unroll
;       for (int rr = 0; rr < RBD; ++rr) {
; #pragma unroll
;         for (int j = 0; j < 4; ++j) x[rr][j] = bf2f(src[(size_t)rr * 1024 + 32 * j]);
;         x[rr][4] = 0.f; x[rr][5] = 0.f;
;       }
;     }
;     float nwv[6];
;     const float* nwp = (isq ? p.in[I_MQQK] : p.in[I_MKQK]) + l * 192 + ln;
; #pragma unroll
;     for (int j = 0; j < 6; ++j) nwv[j] = nwp[32 * j];
;     const float invf = exp2f(-(float)(ln & 15) * (13.287712379549449f / 16.f));
; #pragma unroll
;     for (int rr = 0; rr < RBD; ++rr) {
;       const int t = t0 + rr;
;       const float rstd_in = rsqrtf(hw_sum(ssi[rr]) * (isq ? (1.f / 384.f) : (1.f / 256.f)) + EPS);
.LBB0_218:
	s_or_b64 exec, exec, s[18:19]
	v_readlane_b32 s36, v252, 4
	v_readlane_b32 s41, v252, 9
	v_readlane_b32 s43, v252, 11
	global_load_ushort v89, v[102:103], off
	global_load_ushort v122, v[102:103], off offset:64
	global_load_ushort v123, v[102:103], off offset:128
	s_nop 0
	global_load_ushort v102, v[102:103], off offset:192
	s_nop 0
	global_load_ushort v120, v[100:101], off
	global_load_ushort v117, v[98:99], off
	global_load_ushort v118, v[92:93], off
	global_load_ushort v119, v[104:105], off
	v_readlane_b32 s40, v252, 8
	v_readlane_b32 s42, v252, 10
	v_mov_b32_e32 v92, s43
	v_mov_b32_e32 v93, s41
	v_cndmask_b32_e64 v93, v92, v93, s[22:23]
	v_mov_b32_e32 v92, s42
	v_mov_b32_e32 v98, s40
	v_cndmask_b32_e64 v92, v92, v98, s[22:23]
	v_lshl_add_u64 v[92:93], s[2:3], 2, v[92:93]
	v_lshl_add_u64 v[98:99], v[92:93], 0, v[96:97]
	global_load_dword v103, v[98:99], off
	global_load_dword v104, v[98:99], off offset:128
	global_load_dword v105, v[98:99], off offset:256
	global_load_dword v116, v[98:99], off offset:384
	global_load_dword v93, v[98:99], off offset:512
	global_load_dword v92, v[98:99], off offset:640
	s_waitcnt vmcnt(14)
	v_lshlrev_b32_e32 v94, 16, v200
	v_lshlrev_b32_e32 v95, 16, v201
	v_lshlrev_b32_e32 v90, 16, v202
	v_lshlrev_b32_e32 v91, 16, v203
	ds_bpermute_b32 v98, v107, v88
	v_cndmask_b32_e64 v121, v229, v230, s[22:23]
	v_readlane_b32 s37, v252, 5
	v_readlane_b32 s38, v252, 6
	v_readlane_b32 s39, v252, 7
	s_waitcnt lgkmcnt(0)
	v_add_f32_e32 v88, v88, v98
	s_nop 1
	v_add_f32_dpp v88, v88, v88 row_ror:8 row_mask:0xf bank_mask:0xf
	s_nop 1
	v_add_f32_dpp v88, v88, v88 row_ror:4 row_mask:0xf bank_mask:0xf
	s_nop 1
	v_add_f32_dpp v88, v88, v88 row_ror:2 row_mask:0xf bank_mask:0xf
	s_nop 1
	v_add_f32_dpp v88, v88, v88 row_ror:1 row_mask:0xf bank_mask:0xf
	v_fmaak_f32 v88, v121, v88, 0x358637bd
	v_mul_f32_e32 v98, 0x4b800000, v88
	v_cmp_gt_f32_e32 vcc, s77, v88
	s_waitcnt vmcnt(13)
	v_lshlrev_b32_e32 v89, 16, v89
	v_cndmask_b32_e32 v88, v88, v98, vcc
	v_rsq_f32_e32 v88, v88
	s_waitcnt vmcnt(12)
	v_lshlrev_b32_e32 v99, 16, v122
	s_waitcnt vmcnt(10)
	v_lshlrev_b32_e32 v100, 16, v102
	v_lshlrev_b32_e32 v101, 16, v123
	v_mul_f32_e32 v98, 0x45800000, v88
	v_cndmask_b32_e32 v102, v88, v98, vcc
	v_mul_f32_e32 v98, v102, v89
	v_mul_f32_e32 v99, v102, v99
	s_and_saveexec_b64 s[18:19], s[26:27]
	s_xor_b64 s[18:19], exec, s[18:19]
	s_cbranch_execz .LBB0_220
	v_bfe_u32 v88, v98, 16, 1
	v_add3_u32 v88, v98, v88, s61
	global_store_short_d16_hi v[60:61], v88, off
	v_bfe_u32 v88, v99, 16, 1
	v_add3_u32 v88, v99, v88, s61
	global_store_short_d16_hi v[62:63], v88, off
	v_mul_f32_e32 v88, v102, v101
	v_bfe_u32 v89, v88, 16, 1
	v_add3_u32 v88, v88, v89, s61
	global_store_short_d16_hi v[64:65], v88, off
	v_mul_f32_e32 v88, v102, v100
	v_bfe_u32 v89, v88, 16, 1
	v_add3_u32 v88, v88, v89, s61
	global_store_short_d16_hi v[66:67], v88, off
